# v143 + P6 epilogue Hb residual loads issued one token round ahead, before the previous round's stores (scripts/p6_epi_pipe.py)
# baseline (speedup 1.0000x reference)
.LBB0_394:
	s_or_b64 exec, exec, s[22:23]
	v_lshl_or_b32 v132, s31, 8, v142
	v_lshl_or_b32 v136, s33, 8, v1
	s_waitcnt vmcnt(0)
	s_barrier
	v_mbcnt_lo_u32_b32 v210, -1, 0
	v_mbcnt_hi_u32_b32 v210, -1, v210
	v_bfe_u32 v210, v210, 4, 1
	v_mul_u32_u24_e32 v210, 24, v210
	v_mov_b32_e32 v211, 0
	v_readlane_b32 s48, v249, 16
	v_ashrrev_i32_e32 v133, 31, v132
	v_ashrrev_i32_e32 v137, 31, v136
	v_lshlrev_b64 v[134:135], 11, v[132:133]
	v_lshl_add_u64 v[138:139], s[12:13], 0, v[134:135]
	v_lshlrev_b64 v[134:135], 1, v[136:137]
	v_lshl_add_u64 v[138:139], v[138:139], 0, v[134:135]
	v_lshl_add_u64 v[208:209], v[138:139], 0, v[210:211]
	global_load_dwordx4 v[192:195], v[208:209], off
	global_load_dwordx4 v[196:199], v[208:209], off offset:64
	v_lshl_add_u64 v[208:209], v[138:139], 0, v[210:211]
	global_load_dwordx4 v[200:203], v[208:209], off offset:256
	global_load_dwordx4 v[204:207], v[208:209], off offset:320
	s_nop 0
	v_add_u32_e32 v164, 16, v132
	v_readlane_b32 s60, v249, 28
	v_readlane_b32 s61, v249, 29
	v_lshlrev_b64 v[166:167], 12, v[132:133]
	v_ashrrev_i32_e32 v165, 31, v164
	s_mov_b64 s[24:25], s[60:61]
	v_lshlrev_b64 v[136:137], 2, v[136:137]
	v_lshl_add_u64 v[166:167], s[24:25], 0, v[166:167]
	v_lshlrev_b64 v[168:169], 11, v[164:165]
	v_lshl_add_u64 v[166:167], v[166:167], 0, v[136:137]
	v_lshl_add_u64 v[168:169], s[12:13], 0, v[168:169]
	v_lshl_add_u64 v[168:169], v[168:169], 0, v[134:135]
	v_readlane_b32 s49, v249, 17
	v_readlane_b32 s50, v249, 18
	v_readlane_b32 s51, v249, 19
	v_readlane_b32 s52, v249, 20
	v_readlane_b32 s53, v249, 21
	v_readlane_b32 s54, v249, 22
	v_readlane_b32 s55, v249, 23
	v_readlane_b32 s56, v249, 24
	v_readlane_b32 s57, v249, 25
	v_readlane_b32 s58, v249, 26
	v_readlane_b32 s59, v249, 27
	v_readlane_b32 s62, v249, 30
	v_readlane_b32 s63, v249, 31
	v_lshl_add_u64 v[228:229], v[168:169], 0, v[210:211]
	global_load_dwordx4 v[212:215], v[228:229], off
	global_load_dwordx4 v[216:219], v[228:229], off offset:64
	v_lshl_add_u64 v[228:229], v[168:169], 0, v[210:211]
	global_load_dwordx4 v[220:223], v[228:229], off offset:256
	global_load_dwordx4 v[224:227], v[228:229], off offset:320
	s_waitcnt vmcnt(7)
	v_permlane16_swap_b32_e32 v192, v194
	v_permlane16_swap_b32_e32 v193, v195
	v_lshlrev_b32_e32 v170, 16, v192
	v_and_b32_e32 v171, 0xffff0000, v192
	v_lshlrev_b32_e32 v140, 16, v193
	v_and_b32_e32 v141, 0xffff0000, v193
	s_waitcnt vmcnt(7)
	v_lshlrev_b32_e32 v172, 16, v194
	v_and_b32_e32 v173, 0xffff0000, v194
	v_lshlrev_b32_e32 v152, 16, v195
	v_and_b32_e32 v153, 0xffff0000, v195
	s_waitcnt vmcnt(6)
	v_permlane16_swap_b32_e32 v196, v198
	v_permlane16_swap_b32_e32 v197, v199
	v_lshlrev_b32_e32 v174, 16, v196
	v_and_b32_e32 v175, 0xffff0000, v196
	v_lshlrev_b32_e32 v154, 16, v197
	v_and_b32_e32 v155, 0xffff0000, v197
	s_waitcnt vmcnt(6)
	v_lshlrev_b32_e32 v176, 16, v198
	v_and_b32_e32 v177, 0xffff0000, v198
	v_lshlrev_b32_e32 v156, 16, v199
	v_and_b32_e32 v157, 0xffff0000, v199
	s_waitcnt vmcnt(5)
	v_permlane16_swap_b32_e32 v200, v202
	v_permlane16_swap_b32_e32 v201, v203
	v_lshlrev_b32_e32 v178, 16, v200
	v_and_b32_e32 v179, 0xffff0000, v200
	v_lshlrev_b32_e32 v158, 16, v201
	v_and_b32_e32 v159, 0xffff0000, v201
	s_waitcnt vmcnt(5)
	v_lshlrev_b32_e32 v180, 16, v202
	v_and_b32_e32 v181, 0xffff0000, v202
	v_lshlrev_b32_e32 v160, 16, v203
	v_and_b32_e32 v161, 0xffff0000, v203
	s_waitcnt vmcnt(4)
	v_permlane16_swap_b32_e32 v204, v206
	v_permlane16_swap_b32_e32 v205, v207
	v_lshlrev_b32_e32 v182, 16, v204
	v_and_b32_e32 v183, 0xffff0000, v204
	v_lshlrev_b32_e32 v162, 16, v205
	v_and_b32_e32 v163, 0xffff0000, v205
	s_waitcnt vmcnt(4)
	v_lshlrev_b32_e32 v184, 16, v206
	v_and_b32_e32 v185, 0xffff0000, v206
	v_lshlrev_b32_e32 v138, 16, v207
	v_and_b32_e32 v139, 0xffff0000, v207
	v_pk_add_f32 v[98:99], v[98:99], v[170:171]
	v_pk_add_f32 v[100:101], v[100:101], v[140:141]
	v_pk_add_f32 v[102:103], v[102:103], v[172:173]
	v_pk_add_f32 v[104:105], v[104:105], v[152:153]
	v_pk_add_f32 v[106:107], v[106:107], v[174:175]
	v_pk_add_f32 v[108:109], v[108:109], v[154:155]
	v_pk_add_f32 v[110:111], v[110:111], v[176:177]
	v_pk_add_f32 v[112:113], v[112:113], v[156:157]
	v_pk_add_f32 v[114:115], v[114:115], v[178:179]
	v_pk_add_f32 v[116:117], v[116:117], v[158:159]
	v_pk_add_f32 v[118:119], v[118:119], v[180:181]
	v_pk_add_f32 v[120:121], v[120:121], v[160:161]
	v_pk_add_f32 v[122:123], v[122:123], v[182:183]
	v_pk_add_f32 v[124:125], v[124:125], v[162:163]
	v_pk_add_f32 v[126:127], v[126:127], v[184:185]
	v_pk_add_f32 v[128:129], v[128:129], v[138:139]
	global_store_dwordx4 v[166:167], v[98:101], off
	global_store_dwordx4 v[166:167], v[102:105], off offset:64
	global_store_dwordx4 v[166:167], v[106:109], off offset:128
	global_store_dwordx4 v[166:167], v[110:113], off offset:192
	global_store_dwordx4 v[166:167], v[114:117], off offset:512
	global_store_dwordx4 v[166:167], v[118:121], off offset:576
	global_store_dwordx4 v[166:167], v[122:125], off offset:640
	global_store_dwordx4 v[166:167], v[126:129], off offset:704
	v_add_u32_e32 v114, 0x80, v132
	v_ashrrev_i32_e32 v115, 31, v114
	v_lshlrev_b64 v[116:117], 12, v[164:165]
	v_lshlrev_b64 v[118:119], 11, v[114:115]
	v_lshl_add_u64 v[116:117], s[24:25], 0, v[116:117]
	v_lshl_add_u64 v[118:119], s[12:13], 0, v[118:119]
	v_lshl_add_u64 v[116:117], v[116:117], 0, v[136:137]
	v_lshl_add_u64 v[118:119], v[118:119], 0, v[134:135]
	v_lshl_add_u64 v[208:209], v[118:119], 0, v[210:211]
	global_load_dwordx4 v[192:195], v[208:209], off
	global_load_dwordx4 v[196:199], v[208:209], off offset:64
	v_lshl_add_u64 v[208:209], v[118:119], 0, v[210:211]
	global_load_dwordx4 v[200:203], v[208:209], off offset:256
	global_load_dwordx4 v[204:207], v[208:209], off offset:320
	s_waitcnt vmcnt(15)
	v_permlane16_swap_b32_e32 v212, v214
	v_permlane16_swap_b32_e32 v213, v215
	v_lshlrev_b32_e32 v120, 16, v212
	v_and_b32_e32 v121, 0xffff0000, v212
	v_lshlrev_b32_e32 v98, 16, v213
	v_and_b32_e32 v99, 0xffff0000, v213
	s_waitcnt vmcnt(15)
	v_lshlrev_b32_e32 v122, 16, v214
	v_and_b32_e32 v123, 0xffff0000, v214
	v_lshlrev_b32_e32 v100, 16, v215
	v_and_b32_e32 v101, 0xffff0000, v215
	s_waitcnt vmcnt(14)
	v_permlane16_swap_b32_e32 v216, v218
	v_permlane16_swap_b32_e32 v217, v219
	v_lshlrev_b32_e32 v124, 16, v216
	v_and_b32_e32 v125, 0xffff0000, v216
	v_lshlrev_b32_e32 v102, 16, v217
	v_and_b32_e32 v103, 0xffff0000, v217
	s_waitcnt vmcnt(14)
	v_lshlrev_b32_e32 v126, 16, v218
	v_and_b32_e32 v127, 0xffff0000, v218
	v_lshlrev_b32_e32 v104, 16, v219
	v_and_b32_e32 v105, 0xffff0000, v219
	s_waitcnt vmcnt(13)
	v_permlane16_swap_b32_e32 v220, v222
	v_permlane16_swap_b32_e32 v221, v223
	v_lshlrev_b32_e32 v128, 16, v220
	v_and_b32_e32 v129, 0xffff0000, v220
	v_lshlrev_b32_e32 v106, 16, v221
	v_and_b32_e32 v107, 0xffff0000, v221
	s_waitcnt vmcnt(13)
	v_lshlrev_b32_e32 v138, 16, v222
	v_and_b32_e32 v139, 0xffff0000, v222
	v_lshlrev_b32_e32 v108, 16, v223
	v_and_b32_e32 v109, 0xffff0000, v223
	s_waitcnt vmcnt(12)
	v_permlane16_swap_b32_e32 v224, v226
	v_permlane16_swap_b32_e32 v225, v227
	v_lshlrev_b32_e32 v140, 16, v224
	v_and_b32_e32 v141, 0xffff0000, v224
	v_lshlrev_b32_e32 v110, 16, v225
	v_and_b32_e32 v111, 0xffff0000, v225
	s_waitcnt vmcnt(12)
	v_lshlrev_b32_e32 v152, 16, v226
	v_and_b32_e32 v153, 0xffff0000, v226
	v_lshlrev_b32_e32 v112, 16, v227
	v_and_b32_e32 v113, 0xffff0000, v227
	v_pk_add_f32 v[66:67], v[66:67], v[120:121]
	v_pk_add_f32 v[68:69], v[68:69], v[98:99]
	v_pk_add_f32 v[70:71], v[70:71], v[122:123]
	v_pk_add_f32 v[72:73], v[72:73], v[100:101]
	v_pk_add_f32 v[74:75], v[74:75], v[124:125]
	v_pk_add_f32 v[76:77], v[76:77], v[102:103]
	v_pk_add_f32 v[78:79], v[78:79], v[126:127]
	v_pk_add_f32 v[80:81], v[80:81], v[104:105]
	v_pk_add_f32 v[82:83], v[82:83], v[128:129]
	v_pk_add_f32 v[84:85], v[84:85], v[106:107]
	v_pk_add_f32 v[86:87], v[86:87], v[138:139]
	v_pk_add_f32 v[88:89], v[88:89], v[108:109]
	v_pk_add_f32 v[90:91], v[90:91], v[140:141]
	v_pk_add_f32 v[92:93], v[92:93], v[110:111]
	v_pk_add_f32 v[94:95], v[94:95], v[152:153]
	v_pk_add_f32 v[96:97], v[96:97], v[112:113]
	global_store_dwordx4 v[116:117], v[66:69], off
	global_store_dwordx4 v[116:117], v[70:73], off offset:64
	global_store_dwordx4 v[116:117], v[74:77], off offset:128
	global_store_dwordx4 v[116:117], v[78:81], off offset:192
	global_store_dwordx4 v[116:117], v[82:85], off offset:512
	global_store_dwordx4 v[116:117], v[86:89], off offset:576
	global_store_dwordx4 v[116:117], v[90:93], off offset:640
	global_store_dwordx4 v[116:117], v[94:97], off offset:704
	v_add_u32_e32 v82, 0x90, v132
	v_ashrrev_i32_e32 v83, 31, v82
	v_lshlrev_b64 v[84:85], 12, v[114:115]
	v_lshlrev_b64 v[86:87], 11, v[82:83]
	v_lshl_add_u64 v[84:85], s[24:25], 0, v[84:85]
	v_lshl_add_u64 v[86:87], s[12:13], 0, v[86:87]
	v_lshl_add_u64 v[84:85], v[84:85], 0, v[136:137]
	v_lshl_add_u64 v[86:87], v[86:87], 0, v[134:135]
	v_lshl_add_u64 v[228:229], v[86:87], 0, v[210:211]
	global_load_dwordx4 v[212:215], v[228:229], off
	global_load_dwordx4 v[216:219], v[228:229], off offset:64
	v_lshl_add_u64 v[228:229], v[86:87], 0, v[210:211]
	global_load_dwordx4 v[220:223], v[228:229], off offset:256
	global_load_dwordx4 v[224:227], v[228:229], off offset:320
	s_waitcnt vmcnt(15)
	v_permlane16_swap_b32_e32 v192, v194
	v_permlane16_swap_b32_e32 v193, v195
	v_lshlrev_b32_e32 v88, 16, v192
	v_and_b32_e32 v89, 0xffff0000, v192
	v_lshlrev_b32_e32 v66, 16, v193
	v_and_b32_e32 v67, 0xffff0000, v193
	s_waitcnt vmcnt(15)
	v_lshlrev_b32_e32 v90, 16, v194
	v_and_b32_e32 v91, 0xffff0000, v194
	v_lshlrev_b32_e32 v68, 16, v195
	v_and_b32_e32 v69, 0xffff0000, v195
	s_waitcnt vmcnt(14)
	v_permlane16_swap_b32_e32 v196, v198
	v_permlane16_swap_b32_e32 v197, v199
	v_lshlrev_b32_e32 v92, 16, v196
	v_and_b32_e32 v93, 0xffff0000, v196
	v_lshlrev_b32_e32 v70, 16, v197
	v_and_b32_e32 v71, 0xffff0000, v197
	s_waitcnt vmcnt(14)
	v_lshlrev_b32_e32 v94, 16, v198
	v_and_b32_e32 v95, 0xffff0000, v198
	v_lshlrev_b32_e32 v72, 16, v199
	v_and_b32_e32 v73, 0xffff0000, v199
	s_waitcnt vmcnt(13)
	v_permlane16_swap_b32_e32 v200, v202
	v_permlane16_swap_b32_e32 v201, v203
	v_lshlrev_b32_e32 v96, 16, v200
	v_and_b32_e32 v97, 0xffff0000, v200
	v_lshlrev_b32_e32 v74, 16, v201
	v_and_b32_e32 v75, 0xffff0000, v201
	s_waitcnt vmcnt(13)
	v_lshlrev_b32_e32 v98, 16, v202
	v_and_b32_e32 v99, 0xffff0000, v202
	v_lshlrev_b32_e32 v76, 16, v203
	v_and_b32_e32 v77, 0xffff0000, v203
	s_waitcnt vmcnt(12)
	v_permlane16_swap_b32_e32 v204, v206
	v_permlane16_swap_b32_e32 v205, v207
	v_lshlrev_b32_e32 v100, 16, v204
	v_and_b32_e32 v101, 0xffff0000, v204
	v_lshlrev_b32_e32 v78, 16, v205
	v_and_b32_e32 v79, 0xffff0000, v205
	s_waitcnt vmcnt(12)
	v_lshlrev_b32_e32 v102, 16, v206
	v_and_b32_e32 v103, 0xffff0000, v206
	v_lshlrev_b32_e32 v80, 16, v207
	v_and_b32_e32 v81, 0xffff0000, v207
	v_pk_add_f32 v[34:35], v[34:35], v[88:89]
	v_pk_add_f32 v[36:37], v[36:37], v[66:67]
	v_pk_add_f32 v[38:39], v[38:39], v[90:91]
	v_pk_add_f32 v[40:41], v[40:41], v[68:69]
	v_pk_add_f32 v[42:43], v[42:43], v[92:93]
	v_pk_add_f32 v[44:45], v[44:45], v[70:71]
	v_pk_add_f32 v[46:47], v[46:47], v[94:95]
	v_pk_add_f32 v[48:49], v[48:49], v[72:73]
	v_pk_add_f32 v[50:51], v[50:51], v[96:97]
	v_pk_add_f32 v[52:53], v[52:53], v[74:75]
	v_pk_add_f32 v[54:55], v[54:55], v[98:99]
	v_pk_add_f32 v[56:57], v[56:57], v[76:77]
	v_pk_add_f32 v[58:59], v[58:59], v[100:101]
	v_pk_add_f32 v[60:61], v[60:61], v[78:79]
	v_pk_add_f32 v[62:63], v[62:63], v[102:103]
	v_pk_add_f32 v[64:65], v[64:65], v[80:81]
	global_store_dwordx4 v[84:85], v[34:37], off
	global_store_dwordx4 v[84:85], v[38:41], off offset:64
	global_store_dwordx4 v[84:85], v[42:45], off offset:128
	global_store_dwordx4 v[84:85], v[46:49], off offset:192
	global_store_dwordx4 v[84:85], v[50:53], off offset:512
	global_store_dwordx4 v[84:85], v[54:57], off offset:576
	global_store_dwordx4 v[84:85], v[58:61], off offset:640
	global_store_dwordx4 v[84:85], v[62:65], off offset:704
	v_lshlrev_b64 v[50:51], 12, v[82:83]
	v_lshl_add_u64 v[50:51], s[24:25], 0, v[50:51]
	v_lshl_add_u64 v[50:51], v[50:51], 0, v[136:137]
	s_waitcnt vmcnt(11)
	v_permlane16_swap_b32_e32 v212, v214
	v_permlane16_swap_b32_e32 v213, v215
	v_lshlrev_b32_e32 v52, 16, v212
	v_and_b32_e32 v53, 0xffff0000, v212
	v_lshlrev_b32_e32 v34, 16, v213
	v_and_b32_e32 v35, 0xffff0000, v213
	s_waitcnt vmcnt(11)
	v_lshlrev_b32_e32 v54, 16, v214
	v_and_b32_e32 v55, 0xffff0000, v214
	v_lshlrev_b32_e32 v36, 16, v215
	v_and_b32_e32 v37, 0xffff0000, v215
	s_waitcnt vmcnt(10)
	v_permlane16_swap_b32_e32 v216, v218
	v_permlane16_swap_b32_e32 v217, v219
	v_lshlrev_b32_e32 v56, 16, v216
	v_and_b32_e32 v57, 0xffff0000, v216
	v_lshlrev_b32_e32 v38, 16, v217
	v_and_b32_e32 v39, 0xffff0000, v217
	s_waitcnt vmcnt(10)
	v_lshlrev_b32_e32 v58, 16, v218
	v_and_b32_e32 v59, 0xffff0000, v218
	v_lshlrev_b32_e32 v40, 16, v219
	v_and_b32_e32 v41, 0xffff0000, v219
	s_waitcnt vmcnt(9)
	v_permlane16_swap_b32_e32 v220, v222
	v_permlane16_swap_b32_e32 v221, v223
	v_lshlrev_b32_e32 v60, 16, v220
	v_and_b32_e32 v61, 0xffff0000, v220
	v_lshlrev_b32_e32 v42, 16, v221
	v_and_b32_e32 v43, 0xffff0000, v221
	s_waitcnt vmcnt(9)
	v_lshlrev_b32_e32 v62, 16, v222
	v_and_b32_e32 v63, 0xffff0000, v222
	v_lshlrev_b32_e32 v44, 16, v223
	v_and_b32_e32 v45, 0xffff0000, v223
	s_waitcnt vmcnt(8)
	v_permlane16_swap_b32_e32 v224, v226
	v_permlane16_swap_b32_e32 v225, v227
	v_lshlrev_b32_e32 v64, 16, v224
	v_and_b32_e32 v65, 0xffff0000, v224
	v_lshlrev_b32_e32 v46, 16, v225
	v_and_b32_e32 v47, 0xffff0000, v225
	s_waitcnt vmcnt(8)
	v_lshlrev_b32_e32 v66, 16, v226
	v_and_b32_e32 v67, 0xffff0000, v226
	v_lshlrev_b32_e32 v48, 16, v227
	v_and_b32_e32 v49, 0xffff0000, v227
	v_pk_add_f32 v[2:3], v[2:3], v[52:53]
	v_pk_add_f32 v[4:5], v[4:5], v[34:35]
	v_pk_add_f32 v[6:7], v[6:7], v[54:55]
	v_pk_add_f32 v[8:9], v[8:9], v[36:37]
	v_pk_add_f32 v[10:11], v[10:11], v[56:57]
	v_pk_add_f32 v[12:13], v[12:13], v[38:39]
	v_pk_add_f32 v[14:15], v[14:15], v[58:59]
	v_pk_add_f32 v[16:17], v[16:17], v[40:41]
	v_pk_add_f32 v[18:19], v[18:19], v[60:61]
	v_pk_add_f32 v[20:21], v[20:21], v[42:43]
	v_pk_add_f32 v[26:27], v[26:27], v[62:63]
	v_pk_add_f32 v[28:29], v[28:29], v[44:45]
	v_pk_add_f32 v[30:31], v[30:31], v[64:65]
	v_pk_add_f32 v[32:33], v[32:33], v[46:47]
	v_pk_add_f32 v[22:23], v[22:23], v[66:67]
	v_pk_add_f32 v[24:25], v[24:25], v[48:49]
	global_store_dwordx4 v[50:51], v[2:5], off
	global_store_dwordx4 v[50:51], v[6:9], off offset:64
	global_store_dwordx4 v[50:51], v[10:13], off offset:128
	global_store_dwordx4 v[50:51], v[14:17], off offset:192
	global_store_dwordx4 v[50:51], v[18:21], off offset:512
	global_store_dwordx4 v[50:51], v[26:29], off offset:576
	global_store_dwordx4 v[50:51], v[30:33], off offset:640
	global_store_dwordx4 v[50:51], v[22:25], off offset:704
	s_load_dword s22, s[0:1], 0x0
	s_waitcnt lgkmcnt(0)
	s_add_i32 s10, s22, s10
	s_cmpk_lt_i32 s10, 0x100
	s_cbranch_scc0 .LBB0_401
